# P5 epilogue: first batch of 8 gate loads issued three k-steps before the end of the second GEMM into dead registers (was: after accumulator staging)
# speedup vs baseline: 1.0298x; 1.0031x over previous
; DI void wait_vm0() { asm volatile("s_waitcnt vmcnt(0)" ::: "memory"); }
; DI void bar_() { __builtin_amdgcn_s_barrier(); }
; DI void lds_sync() { wait_lgkm0(); bar_(); }
; #define SB_ __builtin_amdgcn_sched_barrier(0)
; template <int TM, int TN, int WM, int WN, bool SUMSQ, int NST, class AF, class BF, class AFN, class BFN>
; DI void gemm8x(f32x16 (&acc)[TM][TN], AF arow, BF brow, int K, char* smem, float& sumsq, bool pre, bool hasNext, AFN arowN, BFN browN) {
;     ...
;   for (int kt = 0; kt < nk - 1; ++kt) {
;     SB_;
;     if (NST == 2) {
;       const int ko = (kt + 1) * 64;
;       compute(smem + (kt & 1) * STAGE, smem + ((kt + 1) & 1) * STAGE, true, pa0 + ko, pa1 + ko, pa2 + ko, pa3 + ko, pb0 + ko, pb1 + ko, pb2 + ko, pb3 + ko);
;       SB_;
;       wait_vm0(); bar_();
;     } else {
;       const int ko = (kt + 2) * 64; const bool iss = kt + 2 < nk;
;       const int sn = (sc_ == 0) ? 2 : sc_ - 1;
;       compute(smem + sc_ * STAGE, smem + sn * STAGE, iss, pa0 + ko, pa1 + ko, pa2 + ko, pa3 + ko, pb0 + ko, pb1 + ko, pb2 + ko, pb3 + ko);
;       SB_;
;       if (iss) asm volatile("s_waitcnt vmcnt(6)" ::: "memory"); else wait_vm0();
;       bar_();
;       sc_ = (sc_ == 2) ? 0 : sc_ + 1;
;     }
;   }
;   if (NST == 3) {
;     SB_;
;     compute(smem + sc_ * STAGE, smem, false, pa0, pa0, pa0, pa0, pa0, pa0, pa0, pa0);
;     SB_;
;     lds_sync();
; DI void phase5(const Params& p, char* smem) {
;     ...
;         uint4 gav[4], gbv[4];
; #pragma unroll
;         for (int i = 0; i < 4; ++i) {
;           const size_t tok = (size_t)tokTile * 128 + r0 + 16 * (hb * 4 + i);
;           gav[i] = *(const uint4*)(p.pg + tok * 2048 + nt * 256 + ch * 8); gbv[i] = *(const uint4*)(p.pg + tok * 2048 + 1024 + nt * 256 + ch * 8);
.LBB0_657:
	s_or_b64 exec, exec, s[4:5]
	s_lshl_b32 s26, s26, 7
	v_lshl_add_u64 v[218:219], s[26:27], 0, v[168:169]
	v_lshlrev_b64 v[218:219], 12, v[218:219]
	v_lshl_add_u64 v[218:219], s[24:25], 0, v[218:219]
	s_lshl_b32 s98, s61, 9
	s_mov_b32 s99, s27
	v_lshl_add_u64 v[218:219], v[218:219], 0, s[98:99]
	v_mov_b32_e32 v216, v186
	v_mov_b32_e32 v217, v171
	v_lshl_add_u64 v[218:219], v[218:219], 0, v[216:217]
	global_load_dwordx4 v[188:191], v[218:219], off
	global_load_dwordx4 v[192:195], v[218:219], off offset:2048
	s_mov_b32 s99, 0
	s_mov_b32 s98, s53
	v_lshl_add_u64 v[216:217], v[218:219], 0, s[98:99]
	global_load_dwordx4 v[196:199], v[216:217], off
	global_load_dwordx4 v[200:203], v[216:217], off offset:2048
	s_mov_b32 s98, s54
	v_lshl_add_u64 v[216:217], v[218:219], 0, s[98:99]
	global_load_dwordx4 v[234:237], v[216:217], off
	global_load_dwordx4 v[238:241], v[216:217], off offset:2048
	s_mov_b32 s98, s55
	v_lshl_add_u64 v[216:217], v[218:219], 0, s[98:99]
	global_load_dwordx4 v[242:245], v[216:217], off
	global_load_dwordx4 v[246:249], v[216:217], off offset:2048
	v_mfma_f32_32x32x16_bf16 v[112:127], v[160:163], v[164:167], v[112:127]
	v_mfma_f32_32x32x16_bf16 v[96:111], v[160:163], v[148:151], v[96:111]
	v_mfma_f32_32x32x16_bf16 v[80:95], v[144:147], v[164:167], v[80:95]
	v_mfma_f32_32x32x16_bf16 v[64:79], v[144:147], v[148:151], v[64:79]
	s_setprio 0
	s_waitcnt vmcnt(14)
	s_barrier
	ds_read_b128 v[128:131], v225
	ds_read_b128 v[132:135], v225 offset:4096
	ds_read_b128 v[136:139], v233 offset:32768
	ds_read_b128 v[140:143], v233 offset:36864
	ds_read_b128 v[144:147], v227
	ds_read_b128 v[148:151], v227 offset:4096
	ds_read_b128 v[152:155], v232 offset:32768
	ds_read_b128 v[156:159], v232 offset:36864
	s_setprio 1
	s_waitcnt lgkmcnt(0)
	v_mfma_f32_32x32x16_bf16 v[112:127], v[128:131], v[136:139], v[112:127]
	v_mfma_f32_32x32x16_bf16 v[96:111], v[128:131], v[140:143], v[96:111]
	v_mfma_f32_32x32x16_bf16 v[80:95], v[132:135], v[136:139], v[80:95]
	ds_read_b128 v[128:131], v170
	ds_read_b128 v[136:139], v170 offset:4096
	ds_read_b128 v[160:163], v208 offset:32768
	ds_read_b128 v[164:167], v208 offset:36864
	v_mfma_f32_32x32x16_bf16 v[64:79], v[132:135], v[140:143], v[64:79]
	v_mfma_f32_32x32x16_bf16 v[112:127], v[144:147], v[152:155], v[112:127]
	v_mfma_f32_32x32x16_bf16 v[96:111], v[144:147], v[156:159], v[96:111]
	v_mfma_f32_32x32x16_bf16 v[80:95], v[148:151], v[152:155], v[80:95]
	ds_read_b128 v[132:135], v187
	ds_read_b128 v[140:143], v187 offset:4096
	ds_read_b128 v[144:147], v213 offset:32768
	ds_read_b128 v[152:155], v213 offset:36864
	v_mfma_f32_32x32x16_bf16 v[64:79], v[148:151], v[156:159], v[64:79]
	s_waitcnt lgkmcnt(0)
	v_mfma_f32_32x32x16_bf16 v[112:127], v[128:131], v[160:163], v[112:127]
	v_mfma_f32_32x32x16_bf16 v[96:111], v[128:131], v[164:167], v[96:111]
	v_mfma_f32_32x32x16_bf16 v[80:95], v[136:139], v[160:163], v[80:95]
	v_mfma_f32_32x32x16_bf16 v[64:79], v[136:139], v[164:167], v[64:79]
	v_mfma_f32_32x32x16_bf16 v[112:127], v[132:135], v[144:147], v[112:127]
	v_mfma_f32_32x32x16_bf16 v[96:111], v[132:135], v[152:155], v[96:111]
	v_mfma_f32_32x32x16_bf16 v[80:95], v[140:143], v[144:147], v[80:95]
	v_mfma_f32_32x32x16_bf16 v[64:79], v[140:143], v[152:155], v[64:79]
	s_setprio 0
	s_waitcnt vmcnt(8)
	s_barrier
	ds_read_b128 v[128:131], v225 offset:49152
	ds_read_b128 v[132:135], v225 offset:53248
	ds_read_b128 v[136:139], v226
	ds_read_b128 v[140:143], v226 offset:4096
	ds_read_b128 v[144:147], v227 offset:49152
	ds_read_b128 v[148:151], v227 offset:53248
	ds_read_b128 v[152:155], v228
	ds_read_b128 v[156:159], v228 offset:4096
	s_setprio 1
	s_waitcnt lgkmcnt(0)
	v_mfma_f32_32x32x16_bf16 v[112:127], v[128:131], v[136:139], v[112:127]
	v_mfma_f32_32x32x16_bf16 v[96:111], v[128:131], v[140:143], v[96:111]
	v_mfma_f32_32x32x16_bf16 v[80:95], v[132:135], v[136:139], v[80:95]
	ds_read_b128 v[128:131], v170 offset:49152
	ds_read_b128 v[136:139], v170 offset:53248
	ds_read_b128 v[160:163], v229
	ds_read_b128 v[164:167], v229 offset:4096
	v_mfma_f32_32x32x16_bf16 v[64:79], v[132:135], v[140:143], v[64:79]
	v_mfma_f32_32x32x16_bf16 v[112:127], v[144:147], v[152:155], v[112:127]
	v_mfma_f32_32x32x16_bf16 v[96:111], v[144:147], v[156:159], v[96:111]
	v_mfma_f32_32x32x16_bf16 v[80:95], v[148:151], v[152:155], v[80:95]
	ds_read_b128 v[132:135], v187 offset:49152
	ds_read_b128 v[140:143], v187 offset:53248
	ds_read_b128 v[144:147], v230
	ds_read_b128 v[152:155], v230 offset:4096
	v_mfma_f32_32x32x16_bf16 v[64:79], v[148:151], v[156:159], v[64:79]
	s_waitcnt lgkmcnt(0)
	v_mfma_f32_32x32x16_bf16 v[112:127], v[128:131], v[160:163], v[112:127]
	v_mfma_f32_32x32x16_bf16 v[96:111], v[128:131], v[164:167], v[96:111]
	v_mfma_f32_32x32x16_bf16 v[80:95], v[136:139], v[160:163], v[80:95]
	v_mfma_f32_32x32x16_bf16 v[64:79], v[136:139], v[164:167], v[64:79]
	v_mfma_f32_32x32x16_bf16 v[112:127], v[132:135], v[144:147], v[112:127]
	v_mfma_f32_32x32x16_bf16 v[96:111], v[132:135], v[152:155], v[96:111]
	v_mfma_f32_32x32x16_bf16 v[80:95], v[140:143], v[144:147], v[80:95]
	v_mfma_f32_32x32x16_bf16 v[64:79], v[140:143], v[152:155], v[64:79]
	s_setprio 0
	v_mov_b32_e32 v128, v220
	s_waitcnt lgkmcnt(0)
	s_barrier
; DI unsigned pk_bf16(float lo, float hi) { f32x2v v = {lo, hi}; bf16x2v b = __builtin_convertvector(v, bf16x2v); return __builtin_bit_cast(unsigned, b); }
; DI int tid_() { int t = threadIdx.x; asm volatile("" : "+v"(t)); return t; }
; DI void lds_sync() { wait_lgkm0(); bar_(); }
; template <int TM, int TN, int WM, int WN, class F>
; DI void stage_tile(const f32x16 (&acc)[TM][TN], char* tile, int pitch, F f) {
;   const int t = tid_(), lane = t & 63, w = t >> 6, r = lane & 31, hh = lane >> 5;
;   const int wm = w % WM, wn = w / WM;
; #pragma unroll
;   for (int tm = 0; tm < TM; ++tm)
; #pragma unroll
;     for (int tn = 0; tn < TN; ++tn) {
;       char* d = tile + (wn * TN * 32 + tn * 32 + r) * pitch + (wm * TM * 32 + tm * 32 + 4 * hh) * 2;
; #pragma unroll
;       for (int q = 0; q < 4; ++q) {
;         uint2 o; o.x = pk_bf16(f(acc[tm][tn][4 * q]), f(acc[tm][tn][4 * q + 1])); o.y = pk_bf16(f(acc[tm][tn][4 * q + 2]), f(acc[tm][tn][4 * q + 3]));
;         *(uint2*)(d + 16 * q) = o;
;       }
;     }
; }
; DI void phase5(const Params& p, char* smem) {
;     ...
;     {
;       char* t1 = smem; char* t2 = smem + 128 * 528;
;       const int ch = t & 31, r0 = t >> 5;
;       stage_tile<2, 2, 4, 2>(acc1, t1, 528, [](float v) { return v; });
;       stage_tile<2, 2, 4, 2>(acc2, t2, 528, [](float v) { return v; });
;       lds_sync();
	v_cvt_pk_bf16_f32 v32, v32, v33
	v_ashrrev_i32_e32 v129, 6, v128
	v_lshrrev_b32_e32 v131, 30, v129
	v_add_u32_e32 v131, v129, v131
	v_ashrrev_i32_e32 v131, 2, v131
	v_and_b32_e32 v130, 31, v128
	v_mul_i32_i24_e32 v132, 4, v131
	v_lshrrev_b32_e32 v128, 2, v128
	v_sub_u32_e32 v129, v129, v132
	v_and_b32_e32 v128, 8, v128
	v_lshl_or_b32 v130, v131, 6, v130
	v_lshl_or_b32 v128, v129, 7, v128
	v_mad_u64_u32 v[128:129], s[4:5], v130, s47, v[128:129]
	v_cvt_pk_bf16_f32 v33, v34, v35
	v_cvt_pk_bf16_f32 v34, v36, v37
	v_add_u32_e32 v36, 0x4000, v128
	v_cvt_pk_bf16_f32 v0, v0, v1
	v_cvt_pk_bf16_f32 v1, v2, v3
	v_cvt_pk_bf16_f32 v2, v4, v5
	v_cvt_pk_bf16_f32 v3, v6, v7
	v_cvt_pk_bf16_f32 v48, v48, v49
	v_cvt_pk_bf16_f32 v49, v50, v51
	v_cvt_pk_bf16_f32 v50, v52, v53
	v_cvt_pk_bf16_f32 v51, v54, v55
	v_cvt_pk_bf16_f32 v35, v38, v39
	v_cvt_pk_bf16_f32 v16, v16, v17
	v_cvt_pk_bf16_f32 v17, v18, v19
	v_cvt_pk_bf16_f32 v18, v20, v21
	v_cvt_pk_bf16_f32 v19, v22, v23
	s_waitcnt vmcnt(8)
	ds_write2_b64 v36, v[0:1], v[2:3] offset0:72 offset1:74
	v_cvt_pk_bf16_f32 v0, v8, v9
	v_cvt_pk_bf16_f32 v1, v10, v11
	v_cvt_pk_bf16_f32 v2, v12, v13
	v_cvt_pk_bf16_f32 v3, v14, v15
	ds_write2_b64 v128, v[48:49], v[50:51] offset1:2
	v_cvt_pk_bf16_f32 v48, v56, v57
	v_cvt_pk_bf16_f32 v49, v58, v59
	v_cvt_pk_bf16_f32 v50, v60, v61
	v_cvt_pk_bf16_f32 v51, v62, v63
	ds_write2_b64 v36, v[32:33], v[34:35] offset0:64 offset1:66
	v_cvt_pk_bf16_f32 v32, v40, v41
	v_cvt_pk_bf16_f32 v33, v42, v43
	v_cvt_pk_bf16_f32 v34, v44, v45
	v_cvt_pk_bf16_f32 v35, v46, v47
	ds_write2_b64 v128, v[16:17], v[18:19] offset0:8 offset1:10
	v_cvt_pk_bf16_f32 v16, v24, v25
	v_cvt_pk_bf16_f32 v17, v26, v27
	v_cvt_pk_bf16_f32 v18, v28, v29
	v_cvt_pk_bf16_f32 v19, v30, v31
	ds_write2_b64 v36, v[0:1], v[2:3] offset0:76 offset1:78
	v_mov_b32_e32 v0, v220
	ds_write2_b64 v128, v[48:49], v[50:51] offset0:4 offset1:6
	ds_write2_b64 v36, v[32:33], v[34:35] offset0:68 offset1:70
	ds_write2_b64 v128, v[16:17], v[18:19] offset0:12 offset1:14
	v_cvt_pk_bf16_f32 v5, v118, v119
	v_ashrrev_i32_e32 v1, 6, v0
	v_lshrrev_b32_e32 v3, 30, v1
	v_add_u32_e32 v3, v1, v3
	v_ashrrev_i32_e32 v3, 2, v3
	v_and_b32_e32 v2, 31, v0
	v_mul_i32_i24_e32 v4, 4, v3
	v_lshrrev_b32_e32 v0, 2, v0
	v_sub_u32_e32 v1, v1, v4
	v_and_b32_e32 v0, 8, v0
	v_lshl_or_b32 v2, v3, 6, v2
	v_lshl_or_b32 v0, v1, 7, v0
	v_mad_u64_u32 v[0:1], s[4:5], v2, s47, v[0:1]
	v_add_u32_e32 v1, 0x10800, v0
	v_cvt_pk_bf16_f32 v2, v112, v113
	v_cvt_pk_bf16_f32 v3, v114, v115
	v_cvt_pk_bf16_f32 v4, v116, v117
	ds_write2_b64 v1, v[2:3], v[4:5] offset1:2
	v_cvt_pk_bf16_f32 v2, v120, v121
	v_cvt_pk_bf16_f32 v3, v122, v123
	v_cvt_pk_bf16_f32 v4, v124, v125
	v_cvt_pk_bf16_f32 v5, v126, v127
	ds_write2_b64 v1, v[2:3], v[4:5] offset0:4 offset1:6
	v_cvt_pk_bf16_f32 v2, v96, v97
	v_cvt_pk_bf16_f32 v3, v98, v99
	v_cvt_pk_bf16_f32 v4, v100, v101
	v_cvt_pk_bf16_f32 v5, v102, v103
	v_add_u32_e32 v1, 0x4000, v1
	ds_write2_b64 v1, v[2:3], v[4:5] offset0:64 offset1:66
	v_cvt_pk_bf16_f32 v2, v104, v105
	v_cvt_pk_bf16_f32 v3, v106, v107
	v_cvt_pk_bf16_f32 v4, v108, v109
	v_cvt_pk_bf16_f32 v5, v110, v111
	ds_write2_b64 v1, v[2:3], v[4:5] offset0:68 offset1:70
	v_add_u32_e32 v4, 0x10840, v0
	v_cvt_pk_bf16_f32 v0, v80, v81
	v_cvt_pk_bf16_f32 v1, v82, v83
	v_cvt_pk_bf16_f32 v2, v84, v85
	v_cvt_pk_bf16_f32 v3, v86, v87
	ds_write2_b64 v4, v[0:1], v[2:3] offset1:2
	v_cvt_pk_bf16_f32 v0, v88, v89
	v_cvt_pk_bf16_f32 v1, v90, v91
	v_cvt_pk_bf16_f32 v2, v92, v93
	v_cvt_pk_bf16_f32 v3, v94, v95
	ds_write2_b64 v4, v[0:1], v[2:3] offset0:4 offset1:6
	v_cvt_pk_bf16_f32 v0, v64, v65
	v_cvt_pk_bf16_f32 v1, v66, v67
	v_cvt_pk_bf16_f32 v2, v68, v69
	v_cvt_pk_bf16_f32 v3, v70, v71
	v_add_u32_e32 v4, 0x4000, v4
	ds_write2_b64 v4, v[0:1], v[2:3] offset0:64 offset1:66
	v_cvt_pk_bf16_f32 v0, v72, v73
	v_cvt_pk_bf16_f32 v1, v74, v75
	v_cvt_pk_bf16_f32 v2, v76, v77
	v_cvt_pk_bf16_f32 v3, v78, v79
	v_lshl_add_u64 v[52:53], s[26:27], 0, v[168:169]
	ds_write2_b64 v4, v[0:1], v[2:3] offset0:68 offset1:70
	v_lshlrev_b64 v[0:1], 12, v[52:53]
	v_lshl_add_u64 v[0:1], s[24:25], 0, v[0:1]
	s_lshl_b32 s4, s61, 9
	s_mov_b32 s5, s27
	v_lshl_add_u64 v[0:1], v[0:1], 0, s[4:5]
	v_mov_b32_e32 v187, v171
	v_lshl_add_u64 v[16:17], v[0:1], 0, v[186:187]
	s_waitcnt lgkmcnt(0)
	s_barrier
; DI unsigned pk_bf16(float lo, float hi) { f32x2v v = {lo, hi}; bf16x2v b = __builtin_convertvector(v, bf16x2v); return __builtin_bit_cast(unsigned, b); }
; DI float bf_lo(unsigned u) { return __uint_as_float(u << 16); }
; DI float bf_hi(unsigned u) { return __uint_as_float(u & 0xffff0000u); }
; DI void phase5(const Params& p, char* smem) {
;     ...
; #pragma unroll
;       for (int hb = 0; hb < 2; ++hb) {
;         uint4 gav[4], gbv[4];
; #pragma unroll
;         for (int i = 0; i < 4; ++i) {
;           const size_t tok = (size_t)tokTile * 128 + r0 + 16 * (hb * 4 + i);
;           gav[i] = *(const uint4*)(p.pg + tok * 2048 + nt * 256 + ch * 8); gbv[i] = *(const uint4*)(p.pg + tok * 2048 + 1024 + nt * 256 + ch * 8);
;         }
; #pragma unroll
;         for (int i = 0; i < 4; ++i) {
;           const int row = r0 + 16 * (hb * 4 + i);
;           const size_t tok = (size_t)tokTile * 128 + row;
;           const uint4 u1 = *(const uint4*)(t1 + row * 528 + ch * 16), u2 = *(const uint4*)(t2 + row * 528 + ch * 16);
;           const uint4 ga = gav[i], gb = gbv[i];
;           uint4 o;
;           o.x = pk_bf16(bf_lo(ga.x) * bf_lo(u1.x) + bf_lo(gb.x) * bf_lo(u2.x), bf_hi(ga.x) * bf_hi(u1.x) + bf_hi(gb.x) * bf_hi(u2.x));
;           o.y = pk_bf16(bf_lo(ga.y) * bf_lo(u1.y) + bf_lo(gb.y) * bf_lo(u2.y), bf_hi(ga.y) * bf_hi(u1.y) + bf_hi(gb.y) * bf_hi(u2.y));
;           o.z = pk_bf16(bf_lo(ga.z) * bf_lo(u1.z) + bf_lo(gb.z) * bf_lo(u2.z), bf_hi(ga.z) * bf_hi(u1.z) + bf_hi(gb.z) * bf_hi(u2.z));
;           o.w = pk_bf16(bf_lo(ga.w) * bf_lo(u1.w) + bf_lo(gb.w) * bf_lo(u2.w), bf_hi(ga.w) * bf_hi(u1.w) + bf_hi(gb.w) * bf_hi(u2.w));
;           *(uint4*)(p.m + tok * DM + nt * 256 + ch * 8) = o;
;         }
	s_waitcnt vmcnt(0)
	v_mov_b32_e32 v20, v188
	v_mov_b32_e32 v21, v189
	v_mov_b32_e32 v22, v190
	v_mov_b32_e32 v23, v191
	v_mov_b32_e32 v24, v192
	v_mov_b32_e32 v25, v193
	v_mov_b32_e32 v26, v194
	v_mov_b32_e32 v27, v195
	v_add_co_u32_e32 v0, vcc, s53, v16
	v_add_u32_e32 v18, v204, v205
	s_nop 0
	v_addc_co_u32_e32 v1, vcc, 0, v17, vcc
	v_mov_b32_e32 v28, v196
	v_mov_b32_e32 v29, v197
	v_mov_b32_e32 v30, v198
	v_mov_b32_e32 v31, v199
	v_mov_b32_e32 v32, v200
	v_mov_b32_e32 v33, v201
	v_mov_b32_e32 v34, v202
	v_mov_b32_e32 v35, v203
	v_add_co_u32_e32 v0, vcc, s54, v16
	s_add_i32 s60, s60, s95
	s_nop 0
	v_addc_co_u32_e32 v1, vcc, 0, v17, vcc
	v_mov_b32_e32 v12, v234
	v_mov_b32_e32 v13, v235
	v_mov_b32_e32 v14, v236
	v_mov_b32_e32 v15, v237
	v_mov_b32_e32 v8, v238
	v_mov_b32_e32 v9, v239
	v_mov_b32_e32 v10, v240
	v_mov_b32_e32 v11, v241
	v_add_co_u32_e32 v0, vcc, s55, v16
	ds_read_b128 v[36:39], v18
	s_nop 0
	v_addc_co_u32_e32 v1, vcc, 0, v17, vcc
	v_mov_b32_e32 v4, v242
	v_mov_b32_e32 v5, v243
	v_mov_b32_e32 v6, v244
	v_mov_b32_e32 v7, v245
	s_nop 0
	v_mov_b32_e32 v0, v246
	v_mov_b32_e32 v1, v247
	v_mov_b32_e32 v2, v248
	v_mov_b32_e32 v3, v249
	ds_read_b128 v[40:43], v206
	ds_read_b128 v[44:47], v18 offset:8448
	s_waitcnt lgkmcnt(2)
	v_lshlrev_b32_e32 v56, 16, v36
	v_and_b32_e32 v57, 0xffff0000, v36
	v_lshlrev_b32_e32 v36, 16, v37
	s_waitcnt lgkmcnt(1)
	v_lshlrev_b32_e32 v60, 16, v40
	v_and_b32_e32 v61, 0xffff0000, v40
	v_lshlrev_b32_e32 v40, 16, v41
	v_and_b32_e32 v41, 0xffff0000, v41
	v_and_b32_e32 v37, 0xffff0000, v37
	ds_read_b128 v[48:51], v206 offset:8448
	s_cmpk_lt_u32 s60, 0x100
	s_waitcnt vmcnt(7)
	v_lshlrev_b32_e32 v54, 16, v20
	s_waitcnt vmcnt(6)
	v_lshlrev_b32_e32 v58, 16, v24
	v_and_b32_e32 v59, 0xffff0000, v24
	v_and_b32_e32 v55, 0xffff0000, v20
	v_pk_mul_f32 v[58:59], v[58:59], v[60:61]
	v_lshlrev_b32_e32 v24, 16, v25
	v_pk_fma_f32 v[54:55], v[54:55], v[56:57], v[58:59]
	v_and_b32_e32 v25, 0xffff0000, v25
	v_cvt_pk_bf16_f32 v20, v54, v55
	v_lshlrev_b32_e32 v54, 16, v21
	v_and_b32_e32 v55, 0xffff0000, v21
	v_pk_mul_f32 v[24:25], v[24:25], v[40:41]
	v_lshlrev_b32_e32 v40, 16, v26
	v_pk_fma_f32 v[24:25], v[54:55], v[36:37], v[24:25]
	v_lshlrev_b32_e32 v54, 16, v42
	v_and_b32_e32 v41, 0xffff0000, v26
	v_and_b32_e32 v55, 0xffff0000, v42
	v_cvt_pk_bf16_f32 v21, v24, v25
	v_lshlrev_b32_e32 v24, 16, v22
	v_lshlrev_b32_e32 v36, 16, v38
	v_and_b32_e32 v25, 0xffff0000, v22
	v_and_b32_e32 v37, 0xffff0000, v38
	v_pk_mul_f32 v[40:41], v[40:41], v[54:55]
	v_lshlrev_b32_e32 v26, 16, v27
	v_pk_fma_f32 v[24:25], v[24:25], v[36:37], v[40:41]
	v_lshlrev_b32_e32 v36, 16, v39
	v_lshlrev_b32_e32 v38, 16, v43
	v_and_b32_e32 v37, 0xffff0000, v39
	v_and_b32_e32 v27, 0xffff0000, v27
	v_and_b32_e32 v39, 0xffff0000, v43
	v_cvt_pk_bf16_f32 v22, v24, v25
	v_lshlrev_b32_e32 v24, 16, v23
	v_and_b32_e32 v25, 0xffff0000, v23
	v_pk_mul_f32 v[26:27], v[26:27], v[38:39]
	s_waitcnt vmcnt(2)
	v_lshlrev_b32_e32 v42, 16, v8
	v_pk_fma_f32 v[24:25], v[24:25], v[36:37], v[26:27]
	v_lshlrev_b32_e32 v26, 16, v32
	v_cvt_pk_bf16_f32 v23, v24, v25
	v_lshlrev_b64 v[24:25], 11, v[52:53]
	v_lshl_add_u64 v[24:25], s[18:19], 0, v[24:25]
	v_lshl_add_u64 v[24:25], v[24:25], 0, s[4:5]
	v_lshl_add_u64 v[24:25], v[24:25], 0, v[186:187]
	s_waitcnt lgkmcnt(0)
	v_lshlrev_b32_e32 v36, 16, v48
	v_and_b32_e32 v27, 0xffff0000, v32
	v_and_b32_e32 v37, 0xffff0000, v48
	global_store_dwordx4 v[24:25], v[20:23], off
	v_pk_mul_f32 v[26:27], v[26:27], v[36:37]
	v_lshlrev_b32_e32 v32, 16, v49
	v_lshlrev_b32_e32 v20, 16, v28
	v_lshlrev_b32_e32 v22, 16, v44
	v_and_b32_e32 v21, 0xffff0000, v28
	v_and_b32_e32 v23, 0xffff0000, v44
	v_pk_fma_f32 v[20:21], v[20:21], v[22:23], v[26:27]
	v_lshlrev_b32_e32 v22, 16, v29
	v_lshlrev_b32_e32 v28, 16, v33
	v_and_b32_e32 v23, 0xffff0000, v29
	v_and_b32_e32 v29, 0xffff0000, v33
	v_and_b32_e32 v33, 0xffff0000, v49
	v_lshlrev_b32_e32 v26, 16, v45
	v_and_b32_e32 v27, 0xffff0000, v45
	v_pk_mul_f32 v[28:29], v[28:29], v[32:33]
	v_lshlrev_b32_e32 v32, 16, v50
	v_pk_fma_f32 v[22:23], v[22:23], v[26:27], v[28:29]
	v_lshlrev_b32_e32 v28, 16, v34
	v_and_b32_e32 v29, 0xffff0000, v34
	v_and_b32_e32 v33, 0xffff0000, v50
	v_lshl_add_u64 v[24:25], s[26:27], 0, v[174:175]
	v_cvt_pk_bf16_f32 v20, v20, v21
	v_cvt_pk_bf16_f32 v21, v22, v23
	v_lshlrev_b32_e32 v22, 16, v30
	v_lshlrev_b32_e32 v26, 16, v46
	v_and_b32_e32 v23, 0xffff0000, v30
	v_and_b32_e32 v27, 0xffff0000, v46
	v_pk_mul_f32 v[28:29], v[28:29], v[32:33]
	v_lshlrev_b32_e32 v30, 16, v35
	v_pk_fma_f32 v[22:23], v[22:23], v[26:27], v[28:29]
	v_lshlrev_b32_e32 v26, 16, v31
	v_lshlrev_b32_e32 v32, 16, v51
	v_and_b32_e32 v27, 0xffff0000, v31
	v_and_b32_e32 v31, 0xffff0000, v35
	v_and_b32_e32 v33, 0xffff0000, v51
	v_lshlrev_b64 v[24:25], 11, v[24:25]
	v_lshlrev_b32_e32 v28, 16, v47
	v_and_b32_e32 v29, 0xffff0000, v47
	v_pk_mul_f32 v[30:31], v[30:31], v[32:33]
	v_lshl_add_u64 v[24:25], s[18:19], 0, v[24:25]
	v_pk_fma_f32 v[26:27], v[26:27], v[28:29], v[30:31]
	v_lshl_add_u64 v[24:25], v[24:25], 0, s[4:5]
	v_cvt_pk_bf16_f32 v22, v22, v23
	v_cvt_pk_bf16_f32 v23, v26, v27
	v_lshl_add_u64 v[24:25], v[24:25], 0, v[186:187]
	global_store_dwordx4 v[24:25], v[20:23], off
	ds_read_b128 v[24:27], v206 offset:16896
	ds_read_b128 v[32:35], v206 offset:25344
	ds_read_b128 v[20:23], v18 offset:16896
	ds_read_b128 v[28:31], v18 offset:25344
	v_and_b32_e32 v43, 0xffff0000, v8
	s_waitcnt lgkmcnt(3)
	v_lshlrev_b32_e32 v44, 16, v24
	v_and_b32_e32 v45, 0xffff0000, v24
	v_lshlrev_b32_e32 v38, 16, v12
	s_waitcnt lgkmcnt(1)
; DI unsigned pk_bf16(float lo, float hi) { f32x2v v = {lo, hi}; bf16x2v b = __builtin_convertvector(v, bf16x2v); return __builtin_bit_cast(unsigned, b); }
; DI float bf_lo(unsigned u) { return __uint_as_float(u << 16); }
; DI float bf_hi(unsigned u) { return __uint_as_float(u & 0xffff0000u); }
; DI void phase5(const Params& p, char* smem) {
;     ...
; #pragma unroll
;       for (int hb = 0; hb < 2; ++hb) {
;         uint4 gav[4], gbv[4];
; #pragma unroll
;         for (int i = 0; i < 4; ++i) {
;           const size_t tok = (size_t)tokTile * 128 + r0 + 16 * (hb * 4 + i);
;           gav[i] = *(const uint4*)(p.pg + tok * 2048 + nt * 256 + ch * 8); gbv[i] = *(const uint4*)(p.pg + tok * 2048 + 1024 + nt * 256 + ch * 8);
;         }
; #pragma unroll
;         for (int i = 0; i < 4; ++i) {
;           const int row = r0 + 16 * (hb * 4 + i);
;           const size_t tok = (size_t)tokTile * 128 + row;
;           const uint4 u1 = *(const uint4*)(t1 + row * 528 + ch * 16), u2 = *(const uint4*)(t2 + row * 528 + ch * 16);
;           const uint4 ga = gav[i], gb = gbv[i];
;           uint4 o;
;           o.x = pk_bf16(bf_lo(ga.x) * bf_lo(u1.x) + bf_lo(gb.x) * bf_lo(u2.x), bf_hi(ga.x) * bf_hi(u1.x) + bf_hi(gb.x) * bf_hi(u2.x));
;           o.y = pk_bf16(bf_lo(ga.y) * bf_lo(u1.y) + bf_lo(gb.y) * bf_lo(u2.y), bf_hi(ga.y) * bf_hi(u1.y) + bf_hi(gb.y) * bf_hi(u2.y));
;           o.z = pk_bf16(bf_lo(ga.z) * bf_lo(u1.z) + bf_lo(gb.z) * bf_lo(u2.z), bf_hi(ga.z) * bf_hi(u1.z) + bf_hi(gb.z) * bf_hi(u2.z));
;           o.w = pk_bf16(bf_lo(ga.w) * bf_lo(u1.w) + bf_lo(gb.w) * bf_lo(u2.w), bf_hi(ga.w) * bf_hi(u1.w) + bf_hi(gb.w) * bf_hi(u2.w));
;           *(uint4*)(p.m + tok * DM + nt * 256 + ch * 8) = o;
;         }
	v_lshlrev_b32_e32 v40, 16, v20
	v_and_b32_e32 v39, 0xffff0000, v12
	v_and_b32_e32 v41, 0xffff0000, v20
	v_pk_mul_f32 v[42:43], v[42:43], v[44:45]
	v_lshlrev_b32_e32 v24, 16, v25
	v_pk_fma_f32 v[38:39], v[38:39], v[40:41], v[42:43]
	v_and_b32_e32 v25, 0xffff0000, v25
	v_cvt_pk_bf16_f32 v8, v38, v39
	v_lshlrev_b32_e32 v38, 16, v9
	v_and_b32_e32 v39, 0xffff0000, v9
	v_lshlrev_b32_e32 v12, 16, v13
	v_lshlrev_b32_e32 v20, 16, v21
	v_and_b32_e32 v13, 0xffff0000, v13
	v_and_b32_e32 v21, 0xffff0000, v21
	v_pk_mul_f32 v[24:25], v[38:39], v[24:25]
	v_lshlrev_b32_e32 v38, 16, v26
	v_pk_fma_f32 v[12:13], v[12:13], v[20:21], v[24:25]
	v_lshlrev_b32_e32 v24, 16, v10
	v_and_b32_e32 v25, 0xffff0000, v10
	v_and_b32_e32 v39, 0xffff0000, v26
	v_cvt_pk_bf16_f32 v9, v12, v13
	v_lshlrev_b32_e32 v12, 16, v14
	v_lshlrev_b32_e32 v20, 16, v22
	v_and_b32_e32 v13, 0xffff0000, v14
	v_and_b32_e32 v21, 0xffff0000, v22
	v_pk_mul_f32 v[24:25], v[24:25], v[38:39]
	v_lshlrev_b32_e32 v14, 16, v23
	v_pk_fma_f32 v[12:13], v[12:13], v[20:21], v[24:25]
	v_lshlrev_b32_e32 v20, 16, v11
	v_cvt_pk_bf16_f32 v10, v12, v13
	v_lshlrev_b32_e32 v12, 16, v15
	v_lshlrev_b32_e32 v22, 16, v27
	v_and_b32_e32 v13, 0xffff0000, v15
	v_and_b32_e32 v15, 0xffff0000, v23
	v_and_b32_e32 v21, 0xffff0000, v11
	v_and_b32_e32 v23, 0xffff0000, v27
	v_pk_mul_f32 v[20:21], v[20:21], v[22:23]
	v_lshl_add_u64 v[36:37], s[26:27], 0, v[176:177]
	v_pk_fma_f32 v[12:13], v[12:13], v[14:15], v[20:21]
	s_waitcnt vmcnt(2)
	v_lshlrev_b32_e32 v14, 16, v0
	v_cvt_pk_bf16_f32 v11, v12, v13
	v_lshlrev_b64 v[12:13], 11, v[36:37]
	v_lshl_add_u64 v[12:13], s[18:19], 0, v[12:13]
	v_lshl_add_u64 v[12:13], v[12:13], 0, s[4:5]
	v_lshl_add_u64 v[12:13], v[12:13], 0, v[186:187]
	v_lshlrev_b32_e32 v20, 16, v32
	v_and_b32_e32 v15, 0xffff0000, v0
	v_and_b32_e32 v21, 0xffff0000, v32
	global_store_dwordx4 v[12:13], v[8:11], off
	s_waitcnt lgkmcnt(0)
	v_lshlrev_b32_e32 v12, 16, v28
	v_and_b32_e32 v13, 0xffff0000, v28
	v_lshlrev_b32_e32 v10, 16, v4
	v_and_b32_e32 v11, 0xffff0000, v4
	v_pk_mul_f32 v[14:15], v[14:15], v[20:21]
	v_lshlrev_b32_e32 v4, 16, v5
	v_pk_fma_f32 v[10:11], v[10:11], v[12:13], v[14:15]
	v_lshlrev_b32_e32 v12, 16, v1
	v_lshlrev_b32_e32 v14, 16, v33
	v_and_b32_e32 v13, 0xffff0000, v1
	v_and_b32_e32 v15, 0xffff0000, v33
	v_cvt_pk_bf16_f32 v0, v10, v11
	v_lshlrev_b32_e32 v10, 16, v29
	v_and_b32_e32 v5, 0xffff0000, v5
	v_and_b32_e32 v11, 0xffff0000, v29
	v_pk_mul_f32 v[12:13], v[12:13], v[14:15]
	v_lshlrev_b32_e32 v14, 16, v34
	v_pk_fma_f32 v[4:5], v[4:5], v[10:11], v[12:13]
	v_lshlrev_b32_e32 v12, 16, v2
	v_and_b32_e32 v13, 0xffff0000, v2
	v_and_b32_e32 v15, 0xffff0000, v34
	v_cvt_pk_bf16_f32 v1, v4, v5
	v_lshlrev_b32_e32 v4, 16, v6
	v_lshlrev_b32_e32 v10, 16, v30
	v_and_b32_e32 v5, 0xffff0000, v6
	v_and_b32_e32 v11, 0xffff0000, v30
	v_pk_mul_f32 v[12:13], v[12:13], v[14:15]
	v_lshlrev_b32_e32 v6, 16, v31
	v_pk_fma_f32 v[4:5], v[4:5], v[10:11], v[12:13]
	v_lshlrev_b32_e32 v10, 16, v3
	v_lshlrev_b32_e32 v12, 16, v35
	v_and_b32_e32 v11, 0xffff0000, v3
	v_and_b32_e32 v13, 0xffff0000, v35
	v_cvt_pk_bf16_f32 v2, v4, v5
	v_lshlrev_b32_e32 v4, 16, v7
	v_and_b32_e32 v5, 0xffff0000, v7
	v_and_b32_e32 v7, 0xffff0000, v31
	v_pk_mul_f32 v[10:11], v[10:11], v[12:13]
	v_lshl_add_u64 v[8:9], s[26:27], 0, v[178:179]
	v_pk_fma_f32 v[4:5], v[4:5], v[6:7], v[10:11]
	s_nop 0
	v_cvt_pk_bf16_f32 v3, v4, v5
	v_lshlrev_b64 v[4:5], 11, v[8:9]
	v_lshl_add_u64 v[4:5], s[18:19], 0, v[4:5]
	v_lshl_add_u64 v[4:5], v[4:5], 0, s[4:5]
	v_lshl_add_u64 v[4:5], v[4:5], 0, v[186:187]
	global_store_dwordx4 v[4:5], v[0:3], off
	s_nop 1
	v_add_co_u32_e32 v0, vcc, s56, v16
	s_nop 1
	v_addc_co_u32_e32 v1, vcc, 0, v17, vcc
	global_load_dwordx4 v[20:23], v[0:1], off
	global_load_dwordx4 v[24:27], v[0:1], off offset:2048
	v_add_co_u32_e32 v0, vcc, s57, v16
	s_waitcnt vmcnt(1)
	v_lshlrev_b32_e32 v52, 16, v20
	v_addc_co_u32_e32 v1, vcc, 0, v17, vcc
	global_load_dwordx4 v[28:31], v[0:1], off
	global_load_dwordx4 v[32:35], v[0:1], off offset:2048
	v_add_co_u32_e32 v0, vcc, s58, v16
	s_waitcnt vmcnt(2)
	v_lshlrev_b32_e32 v56, 16, v24
	v_addc_co_u32_e32 v1, vcc, 0, v17, vcc
	global_load_dwordx4 v[12:15], v[0:1], off
	global_load_dwordx4 v[8:11], v[0:1], off offset:2048
	v_add_co_u32_e32 v0, vcc, s59, v16
	v_and_b32_e32 v57, 0xffff0000, v24
	s_nop 0
	v_addc_co_u32_e32 v1, vcc, 0, v17, vcc
	global_load_dwordx4 v[4:7], v[0:1], off
	s_nop 0
	global_load_dwordx4 v[0:3], v[0:1], off offset:2048
	ds_read_b128 v[40:43], v206 offset:33792
	ds_read_b128 v[48:51], v206 offset:42240
	ds_read_b128 v[36:39], v18 offset:33792
	ds_read_b128 v[44:47], v18 offset:42240
	v_and_b32_e32 v53, 0xffff0000, v20
	s_waitcnt lgkmcnt(3)
	v_lshlrev_b32_e32 v58, 16, v40
	v_and_b32_e32 v59, 0xffff0000, v40
	s_waitcnt lgkmcnt(1)
; DI unsigned pk_bf16(float lo, float hi) { f32x2v v = {lo, hi}; bf16x2v b = __builtin_convertvector(v, bf16x2v); return __builtin_bit_cast(unsigned, b); }
; DI float bf_lo(unsigned u) { return __uint_as_float(u << 16); }
; DI float bf_hi(unsigned u) { return __uint_as_float(u & 0xffff0000u); }
; DI void phase5(const Params& p, char* smem) {
;     ...
; #pragma unroll
;       for (int hb = 0; hb < 2; ++hb) {
;         uint4 gav[4], gbv[4];
; #pragma unroll
;         for (int i = 0; i < 4; ++i) {
;           const size_t tok = (size_t)tokTile * 128 + r0 + 16 * (hb * 4 + i);
;           gav[i] = *(const uint4*)(p.pg + tok * 2048 + nt * 256 + ch * 8); gbv[i] = *(const uint4*)(p.pg + tok * 2048 + 1024 + nt * 256 + ch * 8);
;         }
; #pragma unroll
;         for (int i = 0; i < 4; ++i) {
;           const int row = r0 + 16 * (hb * 4 + i);
;           const size_t tok = (size_t)tokTile * 128 + row;
;           const uint4 u1 = *(const uint4*)(t1 + row * 528 + ch * 16), u2 = *(const uint4*)(t2 + row * 528 + ch * 16);
;           const uint4 ga = gav[i], gb = gbv[i];
;           uint4 o;
;           o.x = pk_bf16(bf_lo(ga.x) * bf_lo(u1.x) + bf_lo(gb.x) * bf_lo(u2.x), bf_hi(ga.x) * bf_hi(u1.x) + bf_hi(gb.x) * bf_hi(u2.x));
;           o.y = pk_bf16(bf_lo(ga.y) * bf_lo(u1.y) + bf_lo(gb.y) * bf_lo(u2.y), bf_hi(ga.y) * bf_hi(u1.y) + bf_hi(gb.y) * bf_hi(u2.y));
;           o.z = pk_bf16(bf_lo(ga.z) * bf_lo(u1.z) + bf_lo(gb.z) * bf_lo(u2.z), bf_hi(ga.z) * bf_hi(u1.z) + bf_hi(gb.z) * bf_hi(u2.z));
;           o.w = pk_bf16(bf_lo(ga.w) * bf_lo(u1.w) + bf_lo(gb.w) * bf_lo(u2.w), bf_hi(ga.w) * bf_hi(u1.w) + bf_hi(gb.w) * bf_hi(u2.w));
;           *(uint4*)(p.m + tok * DM + nt * 256 + ch * 8) = o;
;         }
	v_lshlrev_b32_e32 v54, 16, v36
	v_and_b32_e32 v55, 0xffff0000, v36
	v_pk_mul_f32 v[56:57], v[56:57], v[58:59]
	v_lshlrev_b32_e32 v24, 16, v25
	v_pk_fma_f32 v[52:53], v[52:53], v[54:55], v[56:57]
	v_lshlrev_b32_e32 v40, 16, v41
	v_and_b32_e32 v25, 0xffff0000, v25
	v_and_b32_e32 v41, 0xffff0000, v41
	v_cvt_pk_bf16_f32 v20, v52, v53
	v_lshlrev_b32_e32 v52, 16, v21
	v_lshlrev_b32_e32 v36, 16, v37
	v_and_b32_e32 v53, 0xffff0000, v21
	v_and_b32_e32 v37, 0xffff0000, v37
	v_pk_mul_f32 v[24:25], v[24:25], v[40:41]
	v_lshlrev_b32_e32 v40, 16, v26
	v_pk_fma_f32 v[24:25], v[52:53], v[36:37], v[24:25]
	v_lshlrev_b32_e32 v52, 16, v42
	v_and_b32_e32 v41, 0xffff0000, v26
	v_and_b32_e32 v53, 0xffff0000, v42
	v_lshl_add_u64 v[16:17], s[26:27], 0, v[172:173]
	v_cvt_pk_bf16_f32 v21, v24, v25
	v_lshlrev_b32_e32 v24, 16, v22
	v_lshlrev_b32_e32 v36, 16, v38
	v_and_b32_e32 v25, 0xffff0000, v22
	v_and_b32_e32 v37, 0xffff0000, v38
	v_pk_mul_f32 v[40:41], v[40:41], v[52:53]
	v_lshlrev_b32_e32 v26, 16, v27
	v_pk_fma_f32 v[24:25], v[24:25], v[36:37], v[40:41]
	v_lshlrev_b32_e32 v36, 16, v39
	v_lshlrev_b32_e32 v38, 16, v43
	v_and_b32_e32 v37, 0xffff0000, v39
	v_and_b32_e32 v27, 0xffff0000, v27
	v_and_b32_e32 v39, 0xffff0000, v43
	v_lshlrev_b64 v[16:17], 11, v[16:17]
	v_cvt_pk_bf16_f32 v22, v24, v25
	v_lshlrev_b32_e32 v24, 16, v23
	v_and_b32_e32 v25, 0xffff0000, v23
	v_pk_mul_f32 v[26:27], v[26:27], v[38:39]
	v_lshl_add_u64 v[16:17], s[18:19], 0, v[16:17]
	v_pk_fma_f32 v[24:25], v[24:25], v[36:37], v[26:27]
	v_lshl_add_u64 v[16:17], v[16:17], 0, s[4:5]
	v_cvt_pk_bf16_f32 v23, v24, v25
	v_lshl_add_u64 v[16:17], v[16:17], 0, v[186:187]
	v_lshlrev_b32_e32 v26, 16, v48
	v_and_b32_e32 v27, 0xffff0000, v48
	global_store_dwordx4 v[16:17], v[20:23], off
	v_lshl_add_u64 v[16:17], s[26:27], 0, v[180:181]
	v_lshlrev_b64 v[16:17], 11, v[16:17]
	s_waitcnt lgkmcnt(0)
	v_lshlrev_b32_e32 v22, 16, v44
	v_and_b32_e32 v23, 0xffff0000, v44
	v_lshl_add_u64 v[16:17], s[18:19], 0, v[16:17]
	v_lshl_add_u64 v[16:17], v[16:17], 0, s[4:5]
	v_lshl_add_u64 v[16:17], v[16:17], 0, v[186:187]
	s_waitcnt vmcnt(6)
	v_lshlrev_b32_e32 v20, 16, v28
	s_waitcnt vmcnt(5)
	v_lshlrev_b32_e32 v24, 16, v32
	v_and_b32_e32 v25, 0xffff0000, v32
	v_and_b32_e32 v21, 0xffff0000, v28
	v_pk_mul_f32 v[24:25], v[24:25], v[26:27]
	v_lshlrev_b32_e32 v26, 16, v33
	v_pk_fma_f32 v[20:21], v[20:21], v[22:23], v[24:25]
	v_lshlrev_b32_e32 v22, 16, v29
	v_lshlrev_b32_e32 v28, 16, v49
	v_and_b32_e32 v23, 0xffff0000, v29
	v_and_b32_e32 v27, 0xffff0000, v33
	v_and_b32_e32 v29, 0xffff0000, v49
	v_lshlrev_b32_e32 v24, 16, v45
	v_and_b32_e32 v25, 0xffff0000, v45
	v_pk_mul_f32 v[26:27], v[26:27], v[28:29]
	v_lshlrev_b32_e32 v28, 16, v50
	v_pk_fma_f32 v[22:23], v[22:23], v[24:25], v[26:27]
	v_lshlrev_b32_e32 v26, 16, v34
	v_and_b32_e32 v27, 0xffff0000, v34
	v_and_b32_e32 v29, 0xffff0000, v50
	v_cvt_pk_bf16_f32 v20, v20, v21
	v_cvt_pk_bf16_f32 v21, v22, v23
	v_lshlrev_b32_e32 v22, 16, v30
	v_lshlrev_b32_e32 v24, 16, v46
	v_and_b32_e32 v23, 0xffff0000, v30
	v_and_b32_e32 v25, 0xffff0000, v46
	v_pk_mul_f32 v[26:27], v[26:27], v[28:29]
	v_lshlrev_b32_e32 v28, 16, v35
	v_pk_fma_f32 v[22:23], v[22:23], v[24:25], v[26:27]
	v_lshlrev_b32_e32 v24, 16, v31
	v_lshlrev_b32_e32 v30, 16, v51
	v_and_b32_e32 v25, 0xffff0000, v31
	v_and_b32_e32 v29, 0xffff0000, v35
	v_and_b32_e32 v31, 0xffff0000, v51
	v_lshlrev_b32_e32 v26, 16, v47
	v_and_b32_e32 v27, 0xffff0000, v47
	v_pk_mul_f32 v[28:29], v[28:29], v[30:31]
	v_cvt_pk_bf16_f32 v22, v22, v23
	v_pk_fma_f32 v[24:25], v[24:25], v[26:27], v[28:29]
	s_waitcnt vmcnt(3)
	v_lshlrev_b32_e32 v38, 16, v8
	v_cvt_pk_bf16_f32 v23, v24, v25
	global_store_dwordx4 v[16:17], v[20:23], off
	ds_read_b128 v[20:23], v18 offset:50688
	ds_read_b128 v[24:27], v206 offset:50688
	v_and_b32_e32 v39, 0xffff0000, v8
	v_lshlrev_b32_e32 v34, 16, v12
	v_and_b32_e32 v35, 0xffff0000, v12
	s_waitcnt lgkmcnt(1)
; DI unsigned pk_bf16(float lo, float hi) { f32x2v v = {lo, hi}; bf16x2v b = __builtin_convertvector(v, bf16x2v); return __builtin_bit_cast(unsigned, b); }
; DI float bf_lo(unsigned u) { return __uint_as_float(u << 16); }
; DI float bf_hi(unsigned u) { return __uint_as_float(u & 0xffff0000u); }
; DI void lds_sync() { wait_lgkm0(); bar_(); }
; DI void phase5(const Params& p, char* smem) {
;     ...
; #pragma unroll
;       for (int hb = 0; hb < 2; ++hb) {
;         uint4 gav[4], gbv[4];
; #pragma unroll
;         for (int i = 0; i < 4; ++i) {
;           const size_t tok = (size_t)tokTile * 128 + r0 + 16 * (hb * 4 + i);
;           gav[i] = *(const uint4*)(p.pg + tok * 2048 + nt * 256 + ch * 8); gbv[i] = *(const uint4*)(p.pg + tok * 2048 + 1024 + nt * 256 + ch * 8);
;         }
; #pragma unroll
;         for (int i = 0; i < 4; ++i) {
;           const int row = r0 + 16 * (hb * 4 + i);
;           const size_t tok = (size_t)tokTile * 128 + row;
;           const uint4 u1 = *(const uint4*)(t1 + row * 528 + ch * 16), u2 = *(const uint4*)(t2 + row * 528 + ch * 16);
;           const uint4 ga = gav[i], gb = gbv[i];
;           uint4 o;
;           o.x = pk_bf16(bf_lo(ga.x) * bf_lo(u1.x) + bf_lo(gb.x) * bf_lo(u2.x), bf_hi(ga.x) * bf_hi(u1.x) + bf_hi(gb.x) * bf_hi(u2.x));
;           o.y = pk_bf16(bf_lo(ga.y) * bf_lo(u1.y) + bf_lo(gb.y) * bf_lo(u2.y), bf_hi(ga.y) * bf_hi(u1.y) + bf_hi(gb.y) * bf_hi(u2.y));
;           o.z = pk_bf16(bf_lo(ga.z) * bf_lo(u1.z) + bf_lo(gb.z) * bf_lo(u2.z), bf_hi(ga.z) * bf_hi(u1.z) + bf_hi(gb.z) * bf_hi(u2.z));
;           o.w = pk_bf16(bf_lo(ga.w) * bf_lo(u1.w) + bf_lo(gb.w) * bf_lo(u2.w), bf_hi(ga.w) * bf_hi(u1.w) + bf_hi(gb.w) * bf_hi(u2.w));
;           *(uint4*)(p.m + tok * DM + nt * 256 + ch * 8) = o;
;         }
;       }
;       lds_sync();
;     }
;   }
	v_lshlrev_b32_e32 v36, 16, v20
	s_waitcnt lgkmcnt(0)
	v_lshlrev_b32_e32 v40, 16, v24
	v_and_b32_e32 v41, 0xffff0000, v24
	v_and_b32_e32 v37, 0xffff0000, v20
	v_pk_mul_f32 v[38:39], v[38:39], v[40:41]
	v_lshlrev_b32_e32 v24, 16, v25
	v_pk_fma_f32 v[34:35], v[34:35], v[36:37], v[38:39]
	v_and_b32_e32 v25, 0xffff0000, v25
	v_cvt_pk_bf16_f32 v8, v34, v35
	v_lshlrev_b32_e32 v34, 16, v9
	v_and_b32_e32 v35, 0xffff0000, v9
	v_lshlrev_b32_e32 v12, 16, v13
	v_lshlrev_b32_e32 v20, 16, v21
	v_and_b32_e32 v13, 0xffff0000, v13
	v_and_b32_e32 v21, 0xffff0000, v21
	v_pk_mul_f32 v[24:25], v[34:35], v[24:25]
	v_lshlrev_b32_e32 v34, 16, v26
	v_pk_fma_f32 v[12:13], v[12:13], v[20:21], v[24:25]
	v_lshlrev_b32_e32 v24, 16, v10
	v_and_b32_e32 v25, 0xffff0000, v10
	v_and_b32_e32 v35, 0xffff0000, v26
	v_cvt_pk_bf16_f32 v9, v12, v13
	v_lshlrev_b32_e32 v12, 16, v14
	v_lshlrev_b32_e32 v20, 16, v22
	v_and_b32_e32 v13, 0xffff0000, v14
	v_and_b32_e32 v21, 0xffff0000, v22
	v_pk_mul_f32 v[24:25], v[24:25], v[34:35]
	v_lshlrev_b32_e32 v14, 16, v23
	v_pk_fma_f32 v[12:13], v[12:13], v[20:21], v[24:25]
	v_lshlrev_b32_e32 v20, 16, v11
	v_cvt_pk_bf16_f32 v10, v12, v13
	v_lshlrev_b32_e32 v12, 16, v15
	v_lshlrev_b32_e32 v22, 16, v27
	v_and_b32_e32 v13, 0xffff0000, v15
	v_and_b32_e32 v15, 0xffff0000, v23
	v_and_b32_e32 v21, 0xffff0000, v11
	v_and_b32_e32 v23, 0xffff0000, v27
	ds_read_b128 v[16:19], v18 offset:59136
	ds_read_b128 v[28:31], v206 offset:59136
	v_pk_mul_f32 v[20:21], v[20:21], v[22:23]
	v_lshl_add_u64 v[32:33], s[26:27], 0, v[182:183]
	v_pk_fma_f32 v[12:13], v[12:13], v[14:15], v[20:21]
	s_waitcnt vmcnt(2)
	v_lshlrev_b32_e32 v14, 16, v0
	v_cvt_pk_bf16_f32 v11, v12, v13
	v_lshlrev_b64 v[12:13], 11, v[32:33]
	v_lshl_add_u64 v[12:13], s[18:19], 0, v[12:13]
	v_lshl_add_u64 v[12:13], v[12:13], 0, s[4:5]
	v_lshl_add_u64 v[12:13], v[12:13], 0, v[186:187]
	s_waitcnt lgkmcnt(0)
	v_lshlrev_b32_e32 v20, 16, v28
	v_and_b32_e32 v15, 0xffff0000, v0
	v_and_b32_e32 v21, 0xffff0000, v28
	global_store_dwordx4 v[12:13], v[8:11], off
	v_lshlrev_b32_e32 v12, 16, v16
	v_and_b32_e32 v13, 0xffff0000, v16
	v_lshlrev_b32_e32 v10, 16, v4
	v_and_b32_e32 v11, 0xffff0000, v4
	v_pk_mul_f32 v[14:15], v[14:15], v[20:21]
	v_lshlrev_b32_e32 v4, 16, v5
	v_pk_fma_f32 v[10:11], v[10:11], v[12:13], v[14:15]
	v_lshlrev_b32_e32 v12, 16, v1
	v_lshlrev_b32_e32 v14, 16, v29
	v_and_b32_e32 v13, 0xffff0000, v1
	v_and_b32_e32 v15, 0xffff0000, v29
	v_cvt_pk_bf16_f32 v0, v10, v11
	v_lshlrev_b32_e32 v10, 16, v17
	v_and_b32_e32 v5, 0xffff0000, v5
	v_and_b32_e32 v11, 0xffff0000, v17
	v_pk_mul_f32 v[12:13], v[12:13], v[14:15]
	v_lshlrev_b32_e32 v14, 16, v30
	v_pk_fma_f32 v[4:5], v[4:5], v[10:11], v[12:13]
	v_lshlrev_b32_e32 v12, 16, v2
	v_and_b32_e32 v13, 0xffff0000, v2
	v_and_b32_e32 v15, 0xffff0000, v30
	v_cvt_pk_bf16_f32 v1, v4, v5
	v_lshlrev_b32_e32 v4, 16, v6
	v_lshlrev_b32_e32 v10, 16, v18
	v_and_b32_e32 v5, 0xffff0000, v6
	v_and_b32_e32 v11, 0xffff0000, v18
	v_pk_mul_f32 v[12:13], v[12:13], v[14:15]
	v_lshlrev_b32_e32 v6, 16, v19
	v_pk_fma_f32 v[4:5], v[4:5], v[10:11], v[12:13]
	v_lshlrev_b32_e32 v10, 16, v3
	v_lshlrev_b32_e32 v12, 16, v31
	v_and_b32_e32 v11, 0xffff0000, v3
	v_and_b32_e32 v13, 0xffff0000, v31
	v_cvt_pk_bf16_f32 v2, v4, v5
	v_lshlrev_b32_e32 v4, 16, v7
	v_and_b32_e32 v5, 0xffff0000, v7
	v_and_b32_e32 v7, 0xffff0000, v19
	v_pk_mul_f32 v[10:11], v[10:11], v[12:13]
	v_lshl_add_u64 v[8:9], s[26:27], 0, v[184:185]
	v_pk_fma_f32 v[4:5], v[4:5], v[6:7], v[10:11]
	s_nop 0
	v_cvt_pk_bf16_f32 v3, v4, v5
	v_lshlrev_b64 v[4:5], 11, v[8:9]
	v_lshl_add_u64 v[4:5], s[18:19], 0, v[4:5]
	v_lshl_add_u64 v[4:5], v[4:5], 0, s[4:5]
	v_lshl_add_u64 v[4:5], v[4:5], 0, v[186:187]
	global_store_dwordx4 v[4:5], v[0:3], off
	s_waitcnt lgkmcnt(0)
	s_barrier
	s_cbranch_scc0 .LBB0_882
